# adds to the thin-product change: norm_mod0 prompt loop software-pipelined (next iteration's two x rows loaded into spare registers during the current pair's normalise/store, counted waits recomputed)
# speedup vs baseline: 1.0023x; 1.0023x over previous
; DI float4 ldnt4(const float* p) { const f32x4 v = __builtin_nontemporal_load((const f32x4*)p); float4 r; r.x = v[0]; r.y = v[1]; r.z = v[2]; r.w = v[3]; return r; }
; DI void phase_norm_mod(const Params& p, const Sub& s, int layer, bool from_out, bf16_t* dst) {
;   const int lane = VTID & 63, wave = VTID >> 6;
;   const float* mod = (const float*)(p.ws + W_MOD);
;   const float* gv = p.norm_g + layer * D;
;   const int stride = s.vg * 4, rhi = s.samp ? M : MP;
;   for (int r = (s.samp ? MP : 0) + s.vb * 4 + wave; r < rhi; r += 2 * stride) {
;     const int rr[2] = {r, (r + stride < rhi) ? r + stride : r};
;     const bool two = r + stride < rhi;
;     float4 v[2][4], g4[4], sh[2][4], sc[2][4];
; #pragma unroll
;     for (int q = 0; q < 2; ++q) {
;       if (from_out) {
;         const bf16_t* srcb = (const bf16_t*)p.out + (size_t)rr[q] * D;
; #pragma unroll
;         for (int i = 0; i < 4; ++i) ld_bf4(srcb + i * 256 + lane * 4, v[q][i].x, v[q][i].y, v[q][i].z, v[q][i].w);
;       } else {
;         const float* src = xrow(p, rr[q]);
; #pragma unroll
;         for (int i = 0; i < 4; ++i) v[q][i] = ldnt4(src + i * 256 + lane * 4);
.LBB0_132:
	s_or_b64 exec, exec, s[4:5]
	s_mov_b32 s0, 0
	s_waitcnt lgkmcnt(0)
	s_barrier
	s_ashr_i32 s1, s0, 31
	v_readlane_b32 s2, v251, 3
	v_readlane_b32 s3, v251, 4
	s_add_u32 s0, s2, s0
	s_addc_u32 s1, s3, s1
	s_load_dwordx4 s[8:11], s[0:1], 0x0
	s_load_dwordx2 s[12:13], s[0:1], 0x40
	s_load_dwordx2 s[2:3], s[0:1], 0xf8
	v_mov_b32_e32 v0, v182
	v_mov_b32_e32 v2, v182
	v_ashrrev_i32_e32 v1, 8, v0
	s_waitcnt lgkmcnt(0)
	s_add_u32 s6, s2, 0x1800000
	s_addc_u32 s7, s3, 0
	v_mov_b32_e32 v0, v182
	s_add_u32 s0, s2, 0x1080000
	v_readlane_b32 s14, v251, 1
	s_addc_u32 s1, s3, 0
	s_lshl_b32 s19, s14, 3
	v_readlane_b32 s14, v251, 7
	v_lshrrev_b32_e32 v2, 6, v2
	s_mov_b32 s26, 0x10000
	v_add_lshl_u32 v1, v1, s14, 2
	v_and_or_b32 v80, v2, 3, v1
	s_mov_b64 s[4:5], 0x1800000
	v_readlane_b32 s15, v251, 2
	v_cmp_gt_i32_e32 vcc, s26, v80
	v_mbcnt_lo_u32_b32 v183, -1, 0
	s_and_saveexec_b64 s[14:15], vcc
	s_xor_b64 s[14:15], exec, s[14:15]
	v_writelane_b32 v251, s19, 8
	s_cbranch_execz .LBB0_138
	v_lshlrev_b32_e32 v1, 2, v0
	v_and_b32_e32 v2, 0xfc, v1
	v_mbcnt_hi_u32_b32 v1, -1, v183
	v_and_b32_e32 v4, 64, v1
	v_xor_b32_e32 v3, 16, v1
	v_add_u32_e32 v4, 64, v4
	v_cmp_lt_i32_e32 vcc, v3, v4
	v_ashrrev_i32_e32 v81, 31, v80
	v_readlane_b32 s16, v251, 1
	v_cndmask_b32_e32 v3, v1, v3, vcc
	v_lshlrev_b32_e32 v102, 2, v3
	v_xor_b32_e32 v3, 32, v1
	v_cmp_lt_i32_e32 vcc, v3, v4
	v_mov_b32_e32 v83, 0
	v_lshlrev_b32_e32 v82, 2, v2
	v_cndmask_b32_e32 v1, v1, v3, vcc
	v_lshlrev_b32_e32 v103, 2, v1
	v_and_b32_e32 v3, 63, v0
	v_lshlrev_b64 v[0:1], 11, v[80:81]
	v_readlane_b32 s17, v251, 2
	s_lshl_b32 s16, s16, 4
	v_lshl_or_b32 v0, v3, 3, v0
	v_lshl_add_u64 v[84:85], s[12:13], 0, v[82:83]
	v_or_b32_e32 v4, 0x100, v2
	v_or_b32_e32 v6, 0x200, v2
	v_or_b32_e32 v8, 0x300, v2
	v_lshlrev_b32_e32 v82, 1, v2
	v_lshlrev_b64 v[88:89], 12, v[80:81]
	s_ashr_i32 s17, s16, 31
	v_lshl_add_u64 v[0:1], s[2:3], 0, v[0:1]
	v_lshl_add_u64 v[86:87], s[6:7], 0, v[82:83]
	v_lshl_or_b32 v88, v3, 4, v88
	s_lshl_b64 s[18:19], s[16:17], 12
	v_lshl_add_u64 v[90:91], v[0:1], 0, s[4:5]
	s_lshl_b64 s[22:23], s[16:17], 11
	s_mov_b64 s[20:21], 0
	s_movk_i32 s17, 0x3000
	s_mov_b64 s[24:25], 0x1000
	v_lshlrev_b32_e32 v82, 2, v2
	v_lshlrev_b32_e32 v92, 2, v4
	v_mov_b32_e32 v93, v83
	v_lshlrev_b32_e32 v94, 2, v6
	v_mov_b32_e32 v95, v83
	v_lshlrev_b32_e32 v96, 2, v8
	v_mov_b32_e32 v97, v83
	v_mov_b32_e32 v81, s11
	v_mov_b32_e32 v104, s9
	v_mov_b32_e32 v105, s10
	v_mov_b32_e32 v106, s8
	v_mov_b64_e32 v[98:99], s[0:1]
	v_mov_b32_e32 v107, 0x358637bd
	s_mov_b32 s27, 0x800000
	s_mov_b32 s28, 0xffff
	s_lshr_b64 s[36:37], s[18:19], 1
	v_lshl_add_u64 v[200:201], s[8:9], 0, v[88:89]
	v_lshl_add_u64 v[202:203], v[200:201], 0, s[36:37]
	global_load_dwordx4 v[204:207], v[200:201], off nt
	global_load_dwordx4 v[208:211], v[200:201], off offset:1024 nt
	global_load_dwordx4 v[212:215], v[200:201], off offset:2048 nt
	global_load_dwordx4 v[216:219], v[200:201], off offset:3072 nt
	global_load_dwordx4 v[220:223], v[202:203], off nt
	global_load_dwordx4 v[224:227], v[202:203], off offset:1024 nt
	global_load_dwordx4 v[228:231], v[202:203], off offset:2048 nt
	global_load_dwordx4 v[232:235], v[202:203], off offset:3072 nt
	s_waitcnt vmcnt(0)
	s_branch .LBB0_135

; DI float4 ldnt4(const float* p) { const f32x4 v = __builtin_nontemporal_load((const f32x4*)p); float4 r; r.x = v[0]; r.y = v[1]; r.z = v[2]; r.w = v[3]; return r; }
; DI void phase_norm_mod(const Params& p, const Sub& s, int layer, bool from_out, bf16_t* dst) {
;     ...
;   for (int r = (s.samp ? MP : 0) + s.vb * 4 + wave; r < rhi; r += 2 * stride) {
;     const int rr[2] = {r, (r + stride < rhi) ? r + stride : r};
;     const bool two = r + stride < rhi;
;     float4 v[2][4], g4[4], sh[2][4], sc[2][4];
; #pragma unroll
;     for (int q = 0; q < 2; ++q) {
;       if (from_out) {
;         const bf16_t* srcb = (const bf16_t*)p.out + (size_t)rr[q] * D;
; #pragma unroll
;         for (int i = 0; i < 4; ++i) ld_bf4(srcb + i * 256 + lane * 4, v[q][i].x, v[q][i].y, v[q][i].z, v[q][i].w);
;       } else {
;         const float* src = xrow(p, rr[q]);
; #pragma unroll
;         for (int i = 0; i < 4; ++i) v[q][i] = ldnt4(src + i * 256 + lane * 4);
;       }
;       const float* mrow = mod + (size_t)(row_bi(rr[q]) * 2 + layer) * 3072;
; #pragma unroll
;       for (int i = 0; i < 4; ++i) { const int c = i * 256 + lane * 4; sh[q][i] = *(const float4*)(mrow + c); sc[q][i] = *(const float4*)(mrow + 1024 + c); }
;     }
; #pragma unroll
;     for (int i = 0; i < 4; ++i) g4[i] = *(const float4*)(gv + i * 256 + lane * 4);
; #pragma unroll
;     for (int q = 0; q < 2; ++q) {
;       float ss = 0.f;
; #pragma unroll
;       for (int i = 0; i < 4; ++i) ss += v[q][i].x * v[q][i].x + v[q][i].y * v[q][i].y + v[q][i].z * v[q][i].z + v[q][i].w * v[q][i].w;
;       ss = wave_sum(ss);
;       const float rs = rsqrtf(ss * (1.0f / D) + EPS);
.LBB0_135:
	s_waitcnt vmcnt(8)
	v_lshl_add_u64 v[0:1], s[8:9], 0, v[88:89]
	v_mov_b64_e32 v[28:29], v[204:205]
	v_mov_b64_e32 v[30:31], v[206:207]
	v_mov_b64_e32 v[24:25], v[208:209]
	v_mov_b64_e32 v[26:27], v[210:211]
	v_mov_b64_e32 v[20:21], v[212:213]
	v_mov_b64_e32 v[22:23], v[214:215]
	s_waitcnt lgkmcnt(0)
	v_mov_b64_e32 v[16:17], v[216:217]
	v_mov_b64_e32 v[18:19], v[218:219]
	v_ashrrev_i32_e32 v32, 12, v80
	v_and_b32_e32 v32, 0xfffffe, v32
	v_readlane_b32 s4, v251, 8
	v_mul_hi_i32_i24_e32 v33, 0x3000, v32
	v_mul_i32_i24_e32 v32, 0x3000, v32
	v_add_u32_e32 v100, s4, v80
	v_lshl_add_u64 v[32:33], s[0:1], 0, v[32:33]
	v_cmp_gt_i32_e32 vcc, s26, v100
	v_lshl_add_u64 v[38:39], v[32:33], 0, s[24:25]
	v_lshl_add_u64 v[40:41], v[38:39], 0, v[82:83]
	v_cndmask_b32_e32 v34, v80, v100, vcc
	global_load_dwordx4 v[12:15], v[84:85], off
	global_load_dwordx4 v[8:11], v[84:85], off offset:1024
	global_load_dwordx4 v[4:7], v[84:85], off offset:2048
	global_load_dwordx4 v[0:3], v[84:85], off offset:3072
	v_add_u32_e32 v42, 0xffff0000, v34
	global_load_dwordx4 v[108:111], v[40:41], off
	v_lshl_add_u64 v[32:33], v[32:33], 0, v[82:83]
	v_cmp_gt_i32_e64 s[4:5], s26, v34
	global_load_dwordx4 v[112:115], v[32:33], off
	v_lshrrev_b32_e32 v40, 4, v42
	v_ashrrev_i32_e32 v35, 31, v34
	v_ashrrev_i32_e32 v43, 13, v34
	v_cndmask_b32_e64 v34, v42, v34, s[4:5]
	v_add_u32_e32 v42, 8, v40
	v_lshl_add_u64 v[40:41], v[38:39], 0, v[92:93]
	global_load_dwordx4 v[116:119], v[32:33], off offset:1024
	global_load_dwordx4 v[120:123], v[32:33], off offset:2048
	global_load_dwordx4 v[124:127], v[32:33], off offset:3072
	global_load_dwordx4 v[128:131], v[40:41], off
	v_cndmask_b32_e64 v35, 0, v35, s[4:5]
	v_cndmask_b32_e64 v37, v81, v104, s[4:5]
	v_cndmask_b32_e64 v36, v105, v106, s[4:5]
	v_lshlrev_b64 v[34:35], 12, v[34:35]
	s_nop 0
	v_lshl_add_u64 v[48:49], v[38:39], 0, v[94:95]
	v_lshl_add_u64 v[34:35], v[36:37], 0, v[34:35]
	v_cndmask_b32_e64 v36, v42, v43, s[4:5]
	v_lshl_add_u64 v[50:51], v[38:39], 0, v[96:97]
	s_nop 0
	v_lshl_add_u64 v[52:53], v[34:35], 0, v[82:83]
	v_lshlrev_b32_e32 v54, 1, v36
	global_load_dwordx4 v[132:135], v[48:49], off
	global_load_dwordx4 v[136:139], v[50:51], off
	v_mov_b64_e32 v[44:45], v[220:221]
	v_mov_b64_e32 v[46:47], v[222:223]
	v_mov_b64_e32 v[40:41], v[224:225]
	v_mov_b64_e32 v[42:43], v[226:227]
	v_mov_b64_e32 v[36:37], v[228:229]
	v_mov_b64_e32 v[38:39], v[230:231]
	v_mov_b64_e32 v[32:33], v[232:233]
	v_mov_b64_e32 v[34:35], v[234:235]
	v_mad_i64_i32 v[48:49], s[4:5], v54, s17, v[98:99]
	v_lshl_add_u64 v[50:51], v[48:49], 0, s[24:25]
	v_lshl_add_u64 v[52:53], v[50:51], 0, v[82:83]
	v_lshl_add_u64 v[54:55], v[50:51], 0, v[92:93]
	v_lshl_add_u64 v[60:61], v[50:51], 0, v[94:95]
	v_lshl_add_u64 v[140:141], v[50:51], 0, v[96:97]
	v_lshl_add_u64 v[48:49], v[48:49], 0, v[82:83]
	s_nop 0
	v_mov_b32_e32 v56, v29
	s_nop 0
	v_mov_b32_e32 v57, v25
	v_mov_b32_e32 v50, v28
	v_mov_b32_e32 v51, v24
	s_nop 0
	v_mov_b32_e32 v66, v21
	s_nop 0
	v_mov_b32_e32 v67, v17
	v_pk_mul_f32 v[56:57], v[56:57], v[56:57]
	v_mov_b32_e32 v58, v30
	v_mov_b32_e32 v59, v26
	v_mov_b32_e32 v64, v20
	v_mov_b32_e32 v65, v16
	v_pk_mul_f32 v[66:67], v[66:67], v[66:67]
	v_pk_fma_f32 v[50:51], v[50:51], v[50:51], v[56:57]
	v_mov_b32_e32 v62, v31
	v_mov_b32_e32 v63, v27
	v_mov_b32_e32 v68, v22
	v_mov_b32_e32 v69, v18
	v_pk_fma_f32 v[56:57], v[64:65], v[64:65], v[66:67]
	v_pk_fma_f32 v[50:51], v[58:59], v[58:59], v[50:51]
	v_mov_b32_e32 v70, v23
	v_mov_b32_e32 v71, v19
	v_pk_fma_f32 v[56:57], v[68:69], v[68:69], v[56:57]
	v_pk_fma_f32 v[50:51], v[62:63], v[62:63], v[50:51]
	v_pk_fma_f32 v[56:57], v[70:71], v[70:71], v[56:57]
	v_add_f32_e32 v50, v50, v51
	v_add_f32_e32 v50, v50, v56
	v_add_f32_e32 v50, v50, v57
	s_waitcnt vmcnt(7)
	v_pk_add_f32 v[108:109], v[108:109], 1.0 op_sel_hi:[1,0]
	v_pk_add_f32 v[110:111], v[110:111], 1.0 op_sel_hi:[1,0]
	v_add_f32_dpp v50, v50, v50 quad_perm:[1,0,3,2] row_mask:0xf bank_mask:0xf bound_ctrl:1
	s_nop 1
	v_add_f32_dpp v50, v50, v50 quad_perm:[2,3,0,1] row_mask:0xf bank_mask:0xf bound_ctrl:1
	s_nop 1
	v_add_f32_dpp v50, v50, v50 row_half_mirror row_mask:0xf bank_mask:0xf bound_ctrl:1
	s_nop 1
	v_add_f32_dpp v62, v50, v50 row_mirror row_mask:0xf bank_mask:0xf bound_ctrl:1
	ds_bpermute_b32 v63, v102, v62
	global_load_dwordx4 v[72:75], v[48:49], off
	global_load_dwordx4 v[64:67], v[48:49], off offset:1024
	global_load_dwordx4 v[56:59], v[48:49], off offset:2048
	s_nop 0
	global_load_dwordx4 v[48:51], v[48:49], off offset:3072
	s_waitcnt lgkmcnt(0)
	v_add_f32_e32 v101, v62, v63
	global_load_dwordx4 v[76:79], v[52:53], off
	global_load_dwordx4 v[68:71], v[54:55], off
	s_nop 0
	global_load_dwordx4 v[60:63], v[60:61], off
	s_nop 0
	global_load_dwordx4 v[52:55], v[140:141], off
	v_add_u32_e32 v200, s16, v80
	v_cmp_ge_i32_e64 s[30:31], s28, v200
	s_lshr_b64 s[36:37], s[18:19], 1
	s_and_saveexec_b64 s[34:35], s[30:31]
	v_lshl_add_u64 v[200:201], s[8:9], 0, v[88:89]
	v_lshl_add_u64 v[200:201], v[200:201], 0, s[18:19]
	v_lshl_add_u64 v[202:203], v[200:201], 0, s[36:37]
	global_load_dwordx4 v[204:207], v[200:201], off nt
	global_load_dwordx4 v[208:211], v[200:201], off offset:1024 nt
	global_load_dwordx4 v[212:215], v[200:201], off offset:2048 nt
	global_load_dwordx4 v[216:219], v[200:201], off offset:3072 nt
	global_load_dwordx4 v[220:223], v[202:203], off nt
	global_load_dwordx4 v[224:227], v[202:203], off offset:1024 nt
	global_load_dwordx4 v[228:231], v[202:203], off offset:2048 nt
	global_load_dwordx4 v[232:235], v[202:203], off offset:3072 nt
	s_or_b64 exec, exec, s[34:35]
	ds_bpermute_b32 v142, v103, v101
	s_waitcnt lgkmcnt(0)
; DI void st_bf4(bf16_t* p, float a, float b, float c, float d) { uint2 v; v.x = pack2(a, b); v.y = pack2(c, d); *(uint2*)p = v; }
; DI void phase_norm_mod(const Params& p, const Sub& s, int layer, bool from_out, bf16_t* dst) {
;     ...
; #pragma unroll
;     for (int q = 0; q < 2; ++q) {
;       float ss = 0.f;
; #pragma unroll
;       for (int i = 0; i < 4; ++i) ss += v[q][i].x * v[q][i].x + v[q][i].y * v[q][i].y + v[q][i].z * v[q][i].z + v[q][i].w * v[q][i].w;
;       ss = wave_sum(ss);
;       const float rs = rsqrtf(ss * (1.0f / D) + EPS);
;       if (q == 0 || two) {
; #pragma unroll
;         for (int i = 0; i < 4; ++i) {
;           const int c = i * 256 + lane * 4;
;           st_bf4(dst + (size_t)rr[q] * D + c, v[q][i].x * rs * g4[i].x * (1.f + sc[q][i].x) + sh[q][i].x, v[q][i].y * rs * g4[i].y * (1.f + sc[q][i].y) + sh[q][i].y,
;                  v[q][i].z * rs * g4[i].z * (1.f + sc[q][i].z) + sh[q][i].z, v[q][i].w * rs * g4[i].w * (1.f + sc[q][i].w) + sh[q][i].w);
;         }
;       }
;     }
	v_add_f32_e32 v101, v101, v142
	v_fmamk_f32 v101, v101, 0x3a800000, v107
	v_mul_f32_e32 v140, 0x4b800000, v101
	v_cmp_gt_f32_e64 s[4:5], s27, v101
	s_nop 1
	v_cndmask_b32_e64 v101, v101, v140, s[4:5]
	v_rsq_f32_e32 v101, v101
	s_nop 0
	v_mul_f32_e32 v140, 0x45800000, v101
	v_cndmask_b32_e64 v140, v101, v140, s[4:5]
	v_pk_mul_f32 v[28:29], v[28:29], v[140:141] op_sel_hi:[1,0]
	v_pk_mul_f32 v[30:31], v[30:31], v[140:141] op_sel_hi:[1,0]
	v_pk_mul_f32 v[28:29], v[12:13], v[28:29]
	v_pk_mul_f32 v[30:31], v[14:15], v[30:31]
	s_waitcnt vmcnt(22)
	v_pk_fma_f32 v[28:29], v[108:109], v[28:29], v[112:113]
	v_pk_fma_f32 v[30:31], v[110:111], v[30:31], v[114:115]
	v_pk_mul_f32 v[24:25], v[24:25], v[140:141] op_sel_hi:[1,0]
	v_cvt_pk_bf16_f32 v28, v28, v29
	v_cvt_pk_bf16_f32 v29, v30, v31
	v_pk_mul_f32 v[24:25], v[8:9], v[24:25]
	s_waitcnt vmcnt(18)
	v_pk_add_f32 v[30:31], v[128:129], 1.0 op_sel_hi:[1,0]
	v_pk_mul_f32 v[26:27], v[26:27], v[140:141] op_sel_hi:[1,0]
	v_pk_fma_f32 v[24:25], v[30:31], v[24:25], v[116:117]
	v_pk_mul_f32 v[26:27], v[10:11], v[26:27]
	v_pk_add_f32 v[30:31], v[130:131], 1.0 op_sel_hi:[1,0]
	v_pk_mul_f32 v[20:21], v[20:21], v[140:141] op_sel_hi:[1,0]
	v_pk_fma_f32 v[26:27], v[30:31], v[26:27], v[118:119]
	v_cvt_pk_bf16_f32 v24, v24, v25
	v_cvt_pk_bf16_f32 v25, v26, v27
	v_pk_mul_f32 v[20:21], v[4:5], v[20:21]
	s_waitcnt vmcnt(17)
	v_pk_add_f32 v[26:27], v[132:133], 1.0 op_sel_hi:[1,0]
	v_pk_mul_f32 v[22:23], v[22:23], v[140:141] op_sel_hi:[1,0]
	v_pk_fma_f32 v[20:21], v[26:27], v[20:21], v[120:121]
	v_pk_mul_f32 v[22:23], v[6:7], v[22:23]
	v_pk_add_f32 v[26:27], v[134:135], 1.0 op_sel_hi:[1,0]
	v_pk_mul_f32 v[16:17], v[16:17], v[140:141] op_sel_hi:[1,0]
	v_pk_fma_f32 v[22:23], v[26:27], v[22:23], v[122:123]
	v_cvt_pk_bf16_f32 v20, v20, v21
	v_cvt_pk_bf16_f32 v21, v22, v23
	v_pk_mul_f32 v[16:17], v[0:1], v[16:17]
	s_waitcnt vmcnt(16)
	v_pk_add_f32 v[22:23], v[136:137], 1.0 op_sel_hi:[1,0]
	global_store_dwordx2 v[90:91], v[28:29], off
	global_store_dwordx2 v[90:91], v[24:25], off offset:512
	v_pk_fma_f32 v[22:23], v[22:23], v[16:17], v[124:125]
	s_waitcnt vmcnt(18)
	v_mul_f32_e32 v16, v45, v45
	s_waitcnt vmcnt(18)
	v_mul_f32_e32 v17, v41, v41
	v_fmac_f32_e32 v16, v44, v44
	v_fmac_f32_e32 v17, v40, v40
	v_fmac_f32_e32 v16, v46, v46
	v_fmac_f32_e32 v17, v42, v42
	v_fmac_f32_e32 v16, v47, v47
	v_fmac_f32_e32 v17, v43, v43
	v_add_f32_e32 v16, v16, v17
	s_waitcnt vmcnt(18)
	v_mul_f32_e32 v17, v37, v37
	v_fmac_f32_e32 v17, v36, v36
	v_fmac_f32_e32 v17, v38, v38
	v_fmac_f32_e32 v17, v39, v39
	v_add_f32_e32 v16, v16, v17
	s_waitcnt vmcnt(18)
	v_mul_f32_e32 v17, v33, v33
	v_fmac_f32_e32 v17, v32, v32
	v_fmac_f32_e32 v17, v34, v34
	v_fmac_f32_e32 v17, v35, v35
	v_add_f32_e32 v16, v16, v17
	global_store_dwordx2 v[90:91], v[20:21], off offset:1024
	v_pk_add_f32 v[20:21], v[138:139], 1.0 op_sel_hi:[1,0]
	v_add_f32_dpp v16, v16, v16 quad_perm:[1,0,3,2] row_mask:0xf bank_mask:0xf bound_ctrl:1
	s_nop 1
	v_add_f32_dpp v16, v16, v16 quad_perm:[2,3,0,1] row_mask:0xf bank_mask:0xf bound_ctrl:1
	s_nop 1
	v_add_f32_dpp v16, v16, v16 row_half_mirror row_mask:0xf bank_mask:0xf bound_ctrl:1
	s_nop 1
	v_add_f32_dpp v24, v16, v16 row_mirror row_mask:0xf bank_mask:0xf bound_ctrl:1
	ds_bpermute_b32 v25, v102, v24
	v_pk_mul_f32 v[16:17], v[18:19], v[140:141] op_sel_hi:[1,0]
	s_nop 0
	v_pk_mul_f32 v[18:19], v[2:3], v[16:17]
	s_waitcnt lgkmcnt(0)
	v_add_f32_e32 v16, v24, v25
	ds_bpermute_b32 v17, v103, v16
	v_pk_fma_f32 v[18:19], v[20:21], v[18:19], v[126:127]
	v_cvt_pk_bf16_f32 v20, v22, v23
	v_cvt_pk_bf16_f32 v21, v18, v19
	global_store_dwordx2 v[90:91], v[20:21], off offset:1536
	s_and_saveexec_b64 s[4:5], vcc
	s_cbranch_execz .LBB0_134
	s_waitcnt lgkmcnt(0)
	v_add_f32_e32 v16, v16, v17
	v_fmamk_f32 v16, v16, 0x3a800000, v107
	v_mul_f32_e32 v17, 0x4b800000, v16
	v_cmp_gt_f32_e32 vcc, s27, v16
	s_waitcnt vmcnt(15)
	v_pk_add_f32 v[20:21], v[76:77], 1.0 op_sel_hi:[1,0]
	v_ashrrev_i32_e32 v101, 31, v100
	v_cndmask_b32_e32 v16, v16, v17, vcc
	v_rsq_f32_e32 v18, v16
	v_lshlrev_b64 v[16:17], 11, v[100:101]
	v_lshl_add_u64 v[16:17], v[86:87], 0, v[16:17]
	v_mul_f32_e32 v19, 0x45800000, v18
	v_cndmask_b32_e32 v18, v18, v19, vcc
	v_pk_mul_f32 v[22:23], v[44:45], v[18:19] op_sel_hi:[1,0]
	s_nop 0
	v_pk_mul_f32 v[12:13], v[12:13], v[22:23]
	v_pk_mul_f32 v[22:23], v[46:47], v[18:19] op_sel_hi:[1,0]
	v_pk_fma_f32 v[12:13], v[20:21], v[12:13], v[72:73]
	v_pk_add_f32 v[20:21], v[78:79], 1.0 op_sel_hi:[1,0]
	v_pk_mul_f32 v[14:15], v[14:15], v[22:23]
	v_cvt_pk_bf16_f32 v12, v12, v13
	v_pk_fma_f32 v[14:15], v[20:21], v[14:15], v[74:75]
	s_nop 0
	v_cvt_pk_bf16_f32 v13, v14, v15
	v_pk_mul_f32 v[14:15], v[40:41], v[18:19] op_sel_hi:[1,0]
	global_store_dwordx2 v[16:17], v[12:13], off
	s_waitcnt vmcnt(15)
	v_pk_add_f32 v[12:13], v[68:69], 1.0 op_sel_hi:[1,0]
	v_pk_mul_f32 v[8:9], v[8:9], v[14:15]
	v_pk_mul_f32 v[14:15], v[42:43], v[18:19] op_sel_hi:[1,0]
	v_pk_fma_f32 v[8:9], v[12:13], v[8:9], v[64:65]
	v_pk_add_f32 v[12:13], v[70:71], 1.0 op_sel_hi:[1,0]
	v_pk_mul_f32 v[10:11], v[10:11], v[14:15]
	v_cvt_pk_bf16_f32 v8, v8, v9
	v_pk_fma_f32 v[10:11], v[12:13], v[10:11], v[66:67]
	s_nop 0
	v_cvt_pk_bf16_f32 v9, v10, v11
	v_pk_mul_f32 v[10:11], v[36:37], v[18:19] op_sel_hi:[1,0]
	global_store_dwordx2 v[16:17], v[8:9], off offset:512
	s_waitcnt vmcnt(15)
	v_pk_add_f32 v[8:9], v[60:61], 1.0 op_sel_hi:[1,0]
	v_pk_mul_f32 v[4:5], v[4:5], v[10:11]
	v_pk_mul_f32 v[10:11], v[38:39], v[18:19] op_sel_hi:[1,0]
	v_pk_fma_f32 v[4:5], v[8:9], v[4:5], v[56:57]
	v_pk_add_f32 v[8:9], v[62:63], 1.0 op_sel_hi:[1,0]
	v_pk_mul_f32 v[6:7], v[6:7], v[10:11]
	v_cvt_pk_bf16_f32 v4, v4, v5
	v_pk_fma_f32 v[6:7], v[8:9], v[6:7], v[58:59]
	s_nop 0
	v_cvt_pk_bf16_f32 v5, v6, v7
	v_pk_mul_f32 v[6:7], v[32:33], v[18:19] op_sel_hi:[1,0]
	global_store_dwordx2 v[16:17], v[4:5], off offset:1024
	s_waitcnt vmcnt(15)
	v_pk_add_f32 v[4:5], v[52:53], 1.0 op_sel_hi:[1,0]
	v_pk_mul_f32 v[0:1], v[0:1], v[6:7]
	v_pk_mul_f32 v[6:7], v[34:35], v[18:19] op_sel_hi:[1,0]
	v_pk_fma_f32 v[0:1], v[4:5], v[0:1], v[48:49]
	v_pk_add_f32 v[4:5], v[54:55], 1.0 op_sel_hi:[1,0]
	v_pk_mul_f32 v[2:3], v[2:3], v[6:7]
	v_cvt_pk_bf16_f32 v0, v0, v1
	v_pk_fma_f32 v[2:3], v[4:5], v[2:3], v[50:51]
	s_nop 0
	v_cvt_pk_bf16_f32 v1, v2, v3
	global_store_dwordx2 v[16:17], v[0:1], off offset:1536
	s_branch .LBB0_134
